# DA (cvt in softmax block): K fragment 0 also fetched at the top of the MFMA block
# speedup vs baseline: 1.0036x; 1.0036x over previous
.LBB0_599:
	s_barrier
	s_setprio 3
	ds_read_b64_tr_b16 v[194:195], v238 offset:0
	ds_read_b64_tr_b16 v[196:197], v238 offset:0x800
	ds_read_b64_tr_b16 v[198:199], v238 offset:0x200
	ds_read_b64_tr_b16 v[200:201], v238 offset:0xa00
	ds_read_b64_tr_b16 v[202:203], v238 offset:0x400
	ds_read_b64_tr_b16 v[204:205], v238 offset:0xc00
	ds_read_b64_tr_b16 v[206:207], v238 offset:0x600
	ds_read_b64_tr_b16 v[208:209], v238 offset:0xe00
	ds_read_b128 v[82:85], v188 offset:40960
	ds_read_b128 v[226:229], v188 offset:45056
	ds_read_b128 v[230:233], v189 offset:40960
	ds_read_b128 v[234:237], v189 offset:45056
	s_waitcnt lgkmcnt(10)
	v_mfma_f32_32x32x16_bf16 v[50:65], v[142:145], v[194:197], v[50:65]
	ds_read_b64_tr_b16 v[210:211], v238 offset:0x1000
	ds_read_b64_tr_b16 v[212:213], v238 offset:0x1800
	s_waitcnt lgkmcnt(10)
	v_mfma_f32_32x32x16_bf16 v[34:49], v[142:145], v[198:201], v[34:49]
	ds_read_b64_tr_b16 v[214:215], v238 offset:0x1200
	ds_read_b64_tr_b16 v[216:217], v238 offset:0x1a00
	s_waitcnt lgkmcnt(10)
	v_mfma_f32_32x32x16_bf16 v[18:33], v[142:145], v[202:205], v[18:33]
	ds_read_b64_tr_b16 v[218:219], v238 offset:0x1400
	ds_read_b64_tr_b16 v[220:221], v238 offset:0x1c00
	s_waitcnt lgkmcnt(10)
	v_mfma_f32_32x32x16_bf16 v[2:17], v[142:145], v[206:209], v[2:17]
	ds_read_b64_tr_b16 v[222:223], v238 offset:0x1600
	ds_read_b64_tr_b16 v[224:225], v238 offset:0x1e00
	v_mfma_f32_16x16x32_bf16 v[244:247], v[142:145], v[248:251], v[244:247]
	s_waitcnt lgkmcnt(6)
	v_mfma_f32_32x32x16_bf16 v[50:65], v[138:141], v[210:213], v[50:65]
	ds_read_b64_tr_b16 v[194:195], v238 offset:0x2000
	ds_read_b64_tr_b16 v[196:197], v238 offset:0x2800
	s_waitcnt lgkmcnt(6)
	v_mfma_f32_32x32x16_bf16 v[34:49], v[138:141], v[214:217], v[34:49]
	ds_read_b64_tr_b16 v[198:199], v238 offset:0x2200
	ds_read_b64_tr_b16 v[200:201], v238 offset:0x2a00
	s_waitcnt lgkmcnt(6)
	v_mfma_f32_32x32x16_bf16 v[18:33], v[138:141], v[218:221], v[18:33]
	ds_read_b64_tr_b16 v[202:203], v238 offset:0x2400
	ds_read_b64_tr_b16 v[204:205], v238 offset:0x2c00
	s_waitcnt lgkmcnt(6)
	v_mfma_f32_32x32x16_bf16 v[2:17], v[138:141], v[222:225], v[2:17]
	ds_read_b64_tr_b16 v[206:207], v238 offset:0x2600
	ds_read_b64_tr_b16 v[208:209], v238 offset:0x2e00
	v_mfma_f32_16x16x32_bf16 v[244:247], v[138:141], v[248:251], v[244:247]
	s_waitcnt lgkmcnt(6)
	v_mfma_f32_32x32x16_bf16 v[50:65], v[134:137], v[194:197], v[50:65]
	ds_read_b64_tr_b16 v[210:211], v238 offset:0x3000
	ds_read_b64_tr_b16 v[212:213], v238 offset:0x3800
	s_waitcnt lgkmcnt(6)
	v_mfma_f32_32x32x16_bf16 v[34:49], v[134:137], v[198:201], v[34:49]
	ds_read_b64_tr_b16 v[214:215], v238 offset:0x3200
	ds_read_b64_tr_b16 v[216:217], v238 offset:0x3a00
	s_waitcnt lgkmcnt(6)
	v_mfma_f32_32x32x16_bf16 v[18:33], v[134:137], v[202:205], v[18:33]
	ds_read_b64_tr_b16 v[218:219], v238 offset:0x3400
	ds_read_b64_tr_b16 v[220:221], v238 offset:0x3c00
	s_waitcnt lgkmcnt(6)
	v_mfma_f32_32x32x16_bf16 v[2:17], v[134:137], v[206:209], v[2:17]
	ds_read_b64_tr_b16 v[222:223], v238 offset:0x3600
	ds_read_b64_tr_b16 v[224:225], v238 offset:0x3e00
	v_mfma_f32_16x16x32_bf16 v[244:247], v[134:137], v[248:251], v[244:247]
	s_waitcnt lgkmcnt(6)
	v_mfma_f32_32x32x16_bf16 v[50:65], v[130:133], v[210:213], v[50:65]
	ds_read_b128 v[194:197], v190 offset:40960
	s_waitcnt lgkmcnt(5)
	v_mfma_f32_32x32x16_bf16 v[34:49], v[130:133], v[214:217], v[34:49]
	ds_read_b128 v[198:201], v190 offset:45056
	s_waitcnt lgkmcnt(4)
	v_mfma_f32_32x32x16_bf16 v[18:33], v[130:133], v[218:221], v[18:33]
	ds_read_b128 v[202:205], v191 offset:40960
	s_waitcnt lgkmcnt(3)
	v_mfma_f32_32x32x16_bf16 v[2:17], v[130:133], v[222:225], v[2:17]
	ds_read_b128 v[206:209], v191 offset:45056
	v_mfma_f32_16x16x32_bf16 v[244:247], v[130:133], v[248:251], v[244:247]
	v_mfma_f32_32x32x16_bf16 v[98:113], v[82:85], v[126:129], v[66:81]
	v_mfma_f32_32x32x16_bf16 v[82:97], v[226:229], v[126:129], v[66:81]
	v_mfma_f32_32x32x16_bf16 v[98:113], v[230:233], v[122:125], v[98:113]
	v_mfma_f32_32x32x16_bf16 v[82:97], v[234:237], v[122:125], v[82:97]
	s_waitcnt lgkmcnt(3)
	v_mfma_f32_32x32x16_bf16 v[98:113], v[194:197], v[118:121], v[98:113]
	s_waitcnt lgkmcnt(2)
	v_mfma_f32_32x32x16_bf16 v[82:97], v[198:201], v[118:121], v[82:97]
	s_waitcnt lgkmcnt(1)
	v_mfma_f32_32x32x16_bf16 v[98:113], v[202:205], v[114:117], v[98:113]
	s_waitcnt lgkmcnt(0)
	v_mfma_f32_32x32x16_bf16 v[82:97], v[206:209], v[114:117], v[82:97]

.LBB0_612:
	s_barrier
	s_setprio 3
	v_add_u32_e32 v197, s75, v193
	ds_read_b64_tr_b16 v[198:199], v197 offset:0
	ds_read_b64_tr_b16 v[200:201], v197 offset:0x800
	ds_read_b64_tr_b16 v[202:203], v197 offset:0x200
	ds_read_b64_tr_b16 v[204:205], v197 offset:0xa00
	ds_read_b64_tr_b16 v[206:207], v197 offset:0x400
	ds_read_b64_tr_b16 v[208:209], v197 offset:0xc00
	ds_read_b64_tr_b16 v[210:211], v197 offset:0x600
	ds_read_b64_tr_b16 v[212:213], v197 offset:0xe00
	ds_read_b128 v[82:85], v188 offset:32768
	ds_read_b128 v[230:233], v188 offset:36864
	ds_read_b128 v[234:237], v189 offset:32768
	ds_read_b128 v[238:241], v189 offset:36864
	s_waitcnt lgkmcnt(10)
	v_mfma_f32_32x32x16_bf16 v[50:65], v[142:145], v[198:201], v[50:65]
	ds_read_b64_tr_b16 v[214:215], v197 offset:0x1000
	ds_read_b64_tr_b16 v[216:217], v197 offset:0x1800
	s_waitcnt lgkmcnt(10)
	v_mfma_f32_32x32x16_bf16 v[34:49], v[142:145], v[202:205], v[34:49]
	ds_read_b64_tr_b16 v[218:219], v197 offset:0x1200
	ds_read_b64_tr_b16 v[220:221], v197 offset:0x1a00
	s_waitcnt lgkmcnt(10)
	v_mfma_f32_32x32x16_bf16 v[18:33], v[142:145], v[206:209], v[18:33]
	ds_read_b64_tr_b16 v[222:223], v197 offset:0x1400
	ds_read_b64_tr_b16 v[224:225], v197 offset:0x1c00
	s_waitcnt lgkmcnt(10)
	v_mfma_f32_32x32x16_bf16 v[2:17], v[142:145], v[210:213], v[2:17]
	ds_read_b64_tr_b16 v[226:227], v197 offset:0x1600
	ds_read_b64_tr_b16 v[228:229], v197 offset:0x1e00
	v_mfma_f32_16x16x32_bf16 v[244:247], v[142:145], v[248:251], v[244:247]
	s_waitcnt lgkmcnt(6)
	v_mfma_f32_32x32x16_bf16 v[50:65], v[138:141], v[214:217], v[50:65]
	ds_read_b64_tr_b16 v[198:199], v197 offset:0x2000
	ds_read_b64_tr_b16 v[200:201], v197 offset:0x2800
	s_waitcnt lgkmcnt(6)
	v_mfma_f32_32x32x16_bf16 v[34:49], v[138:141], v[218:221], v[34:49]
	ds_read_b64_tr_b16 v[202:203], v197 offset:0x2200
	ds_read_b64_tr_b16 v[204:205], v197 offset:0x2a00
	s_waitcnt lgkmcnt(6)
	v_mfma_f32_32x32x16_bf16 v[18:33], v[138:141], v[222:225], v[18:33]
	ds_read_b64_tr_b16 v[206:207], v197 offset:0x2400
	ds_read_b64_tr_b16 v[208:209], v197 offset:0x2c00
	s_waitcnt lgkmcnt(6)
	v_mfma_f32_32x32x16_bf16 v[2:17], v[138:141], v[226:229], v[2:17]
	ds_read_b64_tr_b16 v[210:211], v197 offset:0x2600
	ds_read_b64_tr_b16 v[212:213], v197 offset:0x2e00
	v_mfma_f32_16x16x32_bf16 v[244:247], v[138:141], v[248:251], v[244:247]
	s_waitcnt lgkmcnt(6)
	v_mfma_f32_32x32x16_bf16 v[50:65], v[134:137], v[198:201], v[50:65]
	ds_read_b64_tr_b16 v[214:215], v197 offset:0x3000
	ds_read_b64_tr_b16 v[216:217], v197 offset:0x3800
	s_waitcnt lgkmcnt(6)
	v_mfma_f32_32x32x16_bf16 v[34:49], v[134:137], v[202:205], v[34:49]
	ds_read_b64_tr_b16 v[218:219], v197 offset:0x3200
	ds_read_b64_tr_b16 v[220:221], v197 offset:0x3a00
	s_waitcnt lgkmcnt(6)
	v_mfma_f32_32x32x16_bf16 v[18:33], v[134:137], v[206:209], v[18:33]
	ds_read_b64_tr_b16 v[222:223], v197 offset:0x3400
	ds_read_b64_tr_b16 v[224:225], v197 offset:0x3c00
	s_waitcnt lgkmcnt(6)
	v_mfma_f32_32x32x16_bf16 v[2:17], v[134:137], v[210:213], v[2:17]
	ds_read_b64_tr_b16 v[226:227], v197 offset:0x3600
	ds_read_b64_tr_b16 v[228:229], v197 offset:0x3e00
	v_mfma_f32_16x16x32_bf16 v[244:247], v[134:137], v[248:251], v[244:247]
	s_waitcnt lgkmcnt(6)
	v_mfma_f32_32x32x16_bf16 v[50:65], v[130:133], v[214:217], v[50:65]
	ds_read_b128 v[198:201], v190 offset:32768
	s_waitcnt lgkmcnt(5)
	v_mfma_f32_32x32x16_bf16 v[34:49], v[130:133], v[218:221], v[34:49]
	ds_read_b128 v[202:205], v190 offset:36864
	s_waitcnt lgkmcnt(4)
	v_mfma_f32_32x32x16_bf16 v[18:33], v[130:133], v[222:225], v[18:33]
	ds_read_b128 v[206:209], v191 offset:32768
	s_waitcnt lgkmcnt(3)
	v_mfma_f32_32x32x16_bf16 v[2:17], v[130:133], v[226:229], v[2:17]
	ds_read_b128 v[210:213], v191 offset:36864
	v_mfma_f32_16x16x32_bf16 v[244:247], v[130:133], v[248:251], v[244:247]
	v_mfma_f32_32x32x16_bf16 v[98:113], v[82:85], v[126:129], v[66:81]
	v_mfma_f32_32x32x16_bf16 v[82:97], v[230:233], v[126:129], v[66:81]
	v_mfma_f32_32x32x16_bf16 v[98:113], v[234:237], v[122:125], v[98:113]
	v_mfma_f32_32x32x16_bf16 v[82:97], v[238:241], v[122:125], v[82:97]
	s_waitcnt lgkmcnt(3)
	v_mfma_f32_32x32x16_bf16 v[98:113], v[198:201], v[118:121], v[98:113]
	s_waitcnt lgkmcnt(2)
	v_mfma_f32_32x32x16_bf16 v[82:97], v[202:205], v[118:121], v[82:97]
	s_waitcnt lgkmcnt(1)
	v_mfma_f32_32x32x16_bf16 v[98:113], v[206:209], v[114:117], v[98:113]
	s_waitcnt lgkmcnt(0)
	v_mfma_f32_32x32x16_bf16 v[82:97], v[210:213], v[114:117], v[82:97]
	s_and_b64 vcc, exec, s[6:7]
	s_cbranch_vccnz .LBB0_614
	s_waitcnt vmcnt(1)
